# P1: first two counted waits of each tile relaxed by the 16 epilogue stores that sit in the in-order VMEM queue; K-tile 1 fully landed before the first tile
# baseline (speedup 1.0000x reference)
; #define PG8_STAGE(bufoff, gbase, voff) do { _Pragma("unroll") for (int _i = 0; _i < 2; ++_i) \
;         __builtin_amdgcn_global_load_lds((const unsigned*)((const char*)(gbase) + (voff)[_i]), (PG8_LAS unsigned*)(lds + (bufoff) + ldsw + _i * 8192), 16, 0, 0); } while (0)
; #define PG8_WAIT_V(n) asm volatile("s_waitcnt vmcnt(" #n ")" ::: "memory")
; #define PG8_BAR __builtin_amdgcn_s_barrier()
; template <class Epi, class Sched, bool ALIGN_EPI = false, bool SP2 = false, bool RS = false, bool BPRE = false>
; __device__ __forceinline__ void gemm_phase(PG8_LAS unsigned char* lds, const Gemm g, const Sched& S, const Epi& E, const float* rs_ss = nullptr, PG8_LAS float* rs_tab = nullptr) {
;     ...
;     for (int i = 0; i < 2; ++i) { int R, C; stage_rc(tid * 16 + i * 8192, R, C); const int Rb = (Epi::PERM && !BPRE) ? ((R & ~31) + perm32(R & 31)) : R;
;         voffA[i] = (unsigned)lds_byte(R, C); voffB[i] = (unsigned)lds_byte(Rb, C); }
;     const size_t kstep = (size_t)HTB;
;     const size_t hstep = (size_t)HALF * K * 2;
;     const size_t tstep = 2 * hstep;
;     const unsigned ldsw = (unsigned)wid * 1024u;
;     const int aoff = lds_byte(wr * 64 + fr, fq * 8), boff = lds_byte(wc * 32 + fr, fq * 8);
;     ...
;     if constexpr (SP2) {
;         PG8_STAGE(PG8_SB(0, 0), cB, voffB); PG8_STAGE(PG8_SB(0, 1), cB + hstep, voffB); PG8_STAGE(PG8_SA(0, 0), cA, voffA); PG8_STAGE(PG8_SA(0, 1), cA + hstep, voffA);
;         if (wr == 1) PG8_BAR;
;         PG8_WAIT_V(2); PG8_BAR;
;         PG8_STAGE(PG8_SB(1, 0), cB + kstep, voffB); PG8_STAGE(PG8_SA(1, 0), cA + kstep, voffA); PG8_STAGE(PG8_SB(1, 1), cB + hstep + kstep, voffB);
;         PG8_WAIT_V(6); PG8_BAR;
.LBB0_190:
	s_and_b32 s5, s0, 3
	s_ashr_i32 s77, s3, 31
	s_ashr_i32 s78, s2, 31
	s_lshl_b32 s12, s7, 13
	s_lshl_b32 s13, s5, 12
	s_add_u32 s0, s58, 0x4000
	s_addc_u32 s1, s59, 0
	s_add_i32 m0, s72, 0x18000
	v_lshl_add_u64 v[4:5], s[0:1], 0, v[138:139]
	s_waitcnt vmcnt(2)
	s_barrier
	global_load_lds_dwordx4 v[4:5], off
	s_add_i32 m0, s72, 0x1a000
	v_lshl_add_u64 v[4:5], s[0:1], 0, v[140:141]
	s_add_u32 s0, s56, 0x4000
	s_addc_u32 s1, s57, 0
	s_add_i32 s79, s72, 0x8000
	global_load_lds_dwordx4 v[4:5], off
	v_lshl_add_u64 v[4:5], s[0:1], 0, v[138:139]
	s_mov_b32 m0, s79
	s_add_i32 s80, s72, 0xa000
	global_load_lds_dwordx4 v[4:5], off
	v_lshl_add_u64 v[4:5], s[0:1], 0, v[140:141]
	s_add_u32 s0, s58, 0x84000
	s_mov_b32 m0, s80
	s_addc_u32 s1, s59, 0
	global_load_lds_dwordx4 v[4:5], off
	s_add_i32 m0, s72, 0x1c000
	v_lshl_add_u64 v[4:5], s[0:1], 0, v[138:139]
	global_load_lds_dwordx4 v[4:5], off
	v_lshl_add_u64 v[4:5], s[0:1], 0, v[140:141]
	s_add_i32 m0, s72, 0x1e000
	v_and_b32_e32 v6, 48, v0
	global_load_lds_dwordx4 v[4:5], off
	v_lshlrev_b32_e32 v1, 6, v0
	s_movk_i32 s0, 0x3c0
	v_and_b32_e32 v4, 15, v0
	v_and_or_b32 v7, v1, s0, v6
	v_lshlrev_b32_e32 v1, 2, v0
	v_bfe_u32 v5, v0, 4, 2
	v_and_b32_e32 v8, 32, v1
	v_lshl_or_b32 v1, s7, 6, v4
	v_lshlrev_b32_e32 v4, 6, v4
	v_or_b32_e32 v6, v4, v6
	s_waitcnt vmcnt(6)
	s_cmpk_lt_u32 s6, 0x100
	v_lshl_or_b32 v4, v5, 4, v4
	v_cmp_eq_u32_e64 s[0:1], 0, v5
	v_bitop3_b32 v6, v6, s12, v8 bitop3:0xde
	v_bitop3_b32 v160, s13, v7, v8 bitop3:0xf6
	s_cselect_b64 s[12:13], -1, 0
	s_lshl_b32 s6, s5, 1
	v_lshl_or_b32 v4, s5, 10, v4
	v_mov_b32_e32 v5, v142
	v_add_u32_e32 v146, v2, v3
	s_add_i32 s83, 0, 0x10000
	s_add_i32 s86, 0, 0x14000
	v_mbcnt_lo_u32_b32 v2, -1, 0
	s_or_b32 s81, s6, 0xffffffa0
	v_lshl_add_u64 v[144:145], s[36:37], 0, v[4:5]
	v_mov_b32_e32 v147, v142
	v_mov_b64_e32 v[148:149], 0x700
	v_mov_b64_e32 v[150:151], 0x6ff
	s_movk_i32 s82, 0xe1
	v_add_u32_e32 v161, s83, v160
	v_add_u32_e32 v162, s86, v160
	v_add_u32_e32 v163, 0, v6
	s_mov_b32 s14, 0x3db8aa3b
	v_mbcnt_hi_u32_b32 v164, -1, v2
	s_waitcnt vmcnt(0)
	s_barrier
	s_branch .LBB0_193

; #define PG8_LAS __attribute__((address_space(3)))
; #define PG8_STAGE(bufoff, gbase, voff) do { _Pragma("unroll") for (int _i = 0; _i < 2; ++_i) \
;         __builtin_amdgcn_global_load_lds((const unsigned*)((const char*)(gbase) + (voff)[_i]), (PG8_LAS unsigned*)(lds + (bufoff) + ldsw + _i * 8192), 16, 0, 0); } while (0)
; #define PG8_WAIT_V(n) asm volatile("s_waitcnt vmcnt(" #n ")" ::: "memory")
; #define PG8_BAR __builtin_amdgcn_s_barrier()
; template <class Epi, class Sched, bool ALIGN_EPI = false, bool SP2 = false, bool RS = false, bool BPRE = false>
; __device__ __forceinline__ void gemm_phase(PG8_LAS unsigned char* lds, const Gemm g, const Sched& S, const Epi& E, const float* rs_ss = nullptr, PG8_LAS float* rs_tab = nullptr) {
;     ...
;         const bool has_next = S.next(ui + 1, nxt);
;         const char* nA = has_next ? (const char*)g.A + (size_t)nxt.pm * tstep : cA; const char* nB = has_next ? (const char*)g.Bt + (size_t)nxt.pn * tstep : cB;
;         for (int t = 0; t < nt; t += 2) {
;             const bool last = (t == nt - 2);
;             if constexpr (RS) { if (t == 16 || t == 32) { const PG8_LAS float* tp = rs_tab + (ui & 1) * 768 + (t == 32 ? 256 : 0);
;                 _Pragma("unroll") for (int a = 0; a < 2; ++a) _Pragma("unroll") for (int m = 0; m < 4; ++m) { const float f = tp[a * HALF + wr * 64 + m * 16 + fr];
;                     _Pragma("unroll") for (int b = 0; b < 2; ++b) _Pragma("unroll") for (int n = 0; n < 2; ++n) acc[a][b][m][n] = acc[a][b][m][n] * f; } } }
;             const char* a1 = cA + (size_t)(t + 1) * kstep;
;             const char* a2 = last ? nA : cA + (size_t)(t + 2) * kstep; const char* b2 = last ? nB : cB + (size_t)(t + 2) * kstep;
;             const char* a3 = a2 + kstep; const char* b3 = b2 + kstep;
;             if (last && has_next) S.a_ready(nxt);
;             if constexpr (SP2) {
;             PG8_LDB(B0, 0, 0); PG8_LDB(B1, 0, 1); PG8_SCHED; PG8_LDA(At, 0, 0); PG8_STAGE(PG8_SA(1, 1), a1 + hstep, voffA);
;             PG8_WAIT_V(8); PG8_WAIT_L(0); PG8_BAR; PG8_MMA(0, 0, At, B0); PG8_MMA(0, 1, At, B1); PG8_BAR; PG8_SCHED;
;             PG8_LDA(At, 0, 1); PG8_STAGE(PG8_SB(0, 0), b2, voffB); PG8_STAGE(PG8_SB(0, 1), b2 + hstep, voffB); PG8_STAGE(PG8_SA(0, 0), a2, voffA);
;             PG8_WAIT_V(8); PG8_WAIT_L(0); PG8_BAR; PG8_MMA(1, 0, At, B0); PG8_MMA(1, 1, At, B1); PG8_BAR; PG8_SCHED;
.LBB0_195:
	s_ashr_i32 s19, s18, 31
	s_lshl_b64 s[20:21], s[18:19], 20
	s_add_u32 s20, s30, s20
	s_addc_u32 s21, s31, s21
	s_and_b64 s[44:45], s[6:7], exec
	s_cselect_b32 s5, s21, s57
	s_cselect_b32 s19, s20, s56
	s_ashr_i32 s17, s16, 31
	s_lshl_b64 s[44:45], s[16:17], 20
	s_add_u32 s44, s24, s44
	s_addc_u32 s45, s25, s45
	s_and_b64 s[60:61], s[6:7], exec
	s_cselect_b32 s17, s45, s59
	s_cselect_b32 s47, s44, s58
	s_add_u32 s56, s56, 0x84000
	s_addc_u32 s57, s57, 0
	s_add_u32 s87, s58, 0x8000
	s_addc_u32 s88, s59, 0
	s_mov_b32 s89, -2
	s_waitcnt lgkmcnt(0)
	ds_read_b128 v[130:133], v161
	ds_read_b128 v[134:137], v161 offset:1024
	ds_read_b128 v[152:155], v161 offset:2048
	ds_read_b128 v[156:159], v161 offset:3072
	ds_read_b128 v[166:169], v162
	ds_read_b128 v[170:173], v162 offset:1024
	ds_read_b128 v[174:177], v162 offset:2048
	ds_read_b128 v[182:185], v162 offset:3072
	s_add_u32 s58, s56, 0xfff84000
	s_addc_u32 s59, s57, -1
	s_cmp_eq_u32 s89, 28
	s_cselect_b32 s70, s19, s58
	s_cselect_b32 s71, s5, s59
	s_cselect_b32 s60, s47, s87
	s_cselect_b32 s61, s17, s88
	s_add_u32 s58, s70, 0x4000
	s_addc_u32 s59, s71, 0
	v_lshl_add_u64 v[178:179], s[56:57], 0, v[138:139]
	s_add_i32 m0, s72, 0xc000
	ds_read_b128 v[186:189], v163
	ds_read_b128 v[190:193], v163 offset:1024
	ds_read_b128 v[194:197], v163 offset:2048
	ds_read_b128 v[198:201], v163 offset:3072
	ds_read_b128 v[202:205], v163 offset:4096
	ds_read_b128 v[206:209], v163 offset:5120
	ds_read_b128 v[210:213], v163 offset:6144
	ds_read_b128 v[214:217], v163 offset:7168
	global_load_lds_dwordx4 v[178:179], off
	v_lshl_add_u64 v[178:179], s[56:57], 0, v[146:147]
	s_add_i32 m0, s72, 0xe000
	s_nop 0
	global_load_lds_dwordx4 v[178:179], off
	s_waitcnt vmcnt(24)
	s_waitcnt lgkmcnt(0)
	s_barrier
	s_setprio 1
	s_waitcnt lgkmcnt(0)
	v_mfma_f32_16x16x32_bf16 v[126:129], v[130:133], v[186:189], 0
	v_mfma_f32_16x16x32_bf16 v[122:125], v[152:155], v[186:189], 0
	v_mfma_f32_16x16x32_bf16 v[110:113], v[130:133], v[194:197], 0
	v_mfma_f32_16x16x32_bf16 v[106:109], v[152:155], v[194:197], 0
	v_mfma_f32_16x16x32_bf16 v[94:97], v[130:133], v[202:205], 0
	v_mfma_f32_16x16x32_bf16 v[90:93], v[152:155], v[202:205], 0
	v_mfma_f32_16x16x32_bf16 v[78:81], v[130:133], v[210:213], 0
	v_mfma_f32_16x16x32_bf16 v[74:77], v[152:155], v[210:213], 0
	v_mfma_f32_16x16x32_bf16 v[126:129], v[134:137], v[190:193], v[126:129]
	v_mfma_f32_16x16x32_bf16 v[122:125], v[156:159], v[190:193], v[122:125]
	v_mfma_f32_16x16x32_bf16 v[110:113], v[134:137], v[198:201], v[110:113]
	v_mfma_f32_16x16x32_bf16 v[106:109], v[156:159], v[198:201], v[106:109]
	v_mfma_f32_16x16x32_bf16 v[94:97], v[134:137], v[206:209], v[94:97]
	v_mfma_f32_16x16x32_bf16 v[90:93], v[156:159], v[206:209], v[90:93]
	v_mfma_f32_16x16x32_bf16 v[78:81], v[134:137], v[214:217], v[78:81]
	v_mfma_f32_16x16x32_bf16 v[74:77], v[156:159], v[214:217], v[74:77]
	s_setprio 0
	s_setprio 1
	v_mfma_f32_16x16x32_bf16 v[118:121], v[166:169], v[186:189], 0
	v_mfma_f32_16x16x32_bf16 v[114:117], v[174:177], v[186:189], 0
	v_mfma_f32_16x16x32_bf16 v[102:105], v[166:169], v[194:197], 0
	v_mfma_f32_16x16x32_bf16 v[98:101], v[174:177], v[194:197], 0
	v_mfma_f32_16x16x32_bf16 v[86:89], v[166:169], v[202:205], 0
	v_mfma_f32_16x16x32_bf16 v[82:85], v[174:177], v[202:205], 0
	v_mfma_f32_16x16x32_bf16 v[70:73], v[166:169], v[210:213], 0
	v_mfma_f32_16x16x32_bf16 v[66:69], v[174:177], v[210:213], 0
	v_mfma_f32_16x16x32_bf16 v[118:121], v[170:173], v[190:193], v[118:121]
	v_mfma_f32_16x16x32_bf16 v[114:117], v[182:185], v[190:193], v[114:117]
	v_mfma_f32_16x16x32_bf16 v[102:105], v[170:173], v[198:201], v[102:105]
	v_mfma_f32_16x16x32_bf16 v[98:101], v[182:185], v[198:201], v[98:101]
	v_mfma_f32_16x16x32_bf16 v[86:89], v[170:173], v[206:209], v[86:89]
	v_mfma_f32_16x16x32_bf16 v[82:85], v[182:185], v[206:209], v[82:85]
	v_mfma_f32_16x16x32_bf16 v[70:73], v[170:173], v[214:217], v[70:73]
	v_mfma_f32_16x16x32_bf16 v[66:69], v[182:185], v[214:217], v[66:69]
	s_setprio 0
	s_barrier
	s_add_i32 s90, s83, s15
	v_lshl_add_u64 v[178:179], s[60:61], 0, v[138:139]
	s_mov_b32 m0, s90
	ds_read_b128 v[186:189], v163 offset:16384
	ds_read_b128 v[190:193], v163 offset:17408
	ds_read_b128 v[194:197], v163 offset:18432
	ds_read_b128 v[198:201], v163 offset:19456
	ds_read_b128 v[202:205], v163 offset:20480
	ds_read_b128 v[206:209], v163 offset:21504
	ds_read_b128 v[210:213], v163 offset:22528
	ds_read_b128 v[214:217], v163 offset:23552
	global_load_lds_dwordx4 v[178:179], off
	s_add_i32 m0, s90, 0x2000
	s_add_u32 s90, s60, 0x80000
	v_lshl_add_u64 v[178:179], s[60:61], 0, v[140:141]
	s_addc_u32 s91, s61, 0
	s_add_i32 s92, s86, s15
	global_load_lds_dwordx4 v[178:179], off
	v_lshl_add_u64 v[178:179], s[90:91], 0, v[138:139]
	s_mov_b32 m0, s92
	s_nop 0
	global_load_lds_dwordx4 v[178:179], off
	v_lshl_add_u64 v[178:179], s[90:91], 0, v[140:141]
	s_add_i32 m0, s92, 0x2000
	s_nop 0
	global_load_lds_dwordx4 v[178:179], off
	v_lshl_add_u64 v[178:179], s[70:71], 0, v[138:139]
	s_mov_b32 m0, s72
	s_nop 0
	global_load_lds_dwordx4 v[178:179], off
	v_lshl_add_u64 v[178:179], s[70:71], 0, v[140:141]
	s_mov_b32 m0, s73
	s_nop 0
	global_load_lds_dwordx4 v[178:179], off
	s_waitcnt vmcnt(24)
	s_waitcnt lgkmcnt(0)
	s_barrier
; #define PG8_STAGE(bufoff, gbase, voff) do { _Pragma("unroll") for (int _i = 0; _i < 2; ++_i) \
;         __builtin_amdgcn_global_load_lds((const unsigned*)((const char*)(gbase) + (voff)[_i]), (PG8_LAS unsigned*)(lds + (bufoff) + ldsw + _i * 8192), 16, 0, 0); } while (0)
; #define PG8_LDA(dst, b, h) do { _Pragma("unroll") for (int m = 0; m < 4; ++m) _Pragma("unroll") for (int k = 0; k < 2; ++k) dst[m][k] = *(const PG8_LAS bf16x8*)(lds + PG8_SA(b, h) + aoff + m * 2048 + k * 1024); } while (0)
; #define PG8_LDB(dst, b, h) do { _Pragma("unroll") for (int n = 0; n < 2; ++n) _Pragma("unroll") for (int k = 0; k < 2; ++k) dst[n][k] = *(const PG8_LAS bf16x8*)(lds + PG8_SB(b, h) + boff + n * 2048 + k * 1024); } while (0)
; #define PG8_MMA(ai, bj, At, Bt) do { __builtin_amdgcn_s_setprio(1); _Pragma("unroll") for (int m = 0; m < 4; ++m) _Pragma("unroll") for (int n = 0; n < 2; ++n) _Pragma("unroll") for (int k = 0; k < 2; ++k) \
;         acc[ai][bj][m][n] = __builtin_amdgcn_mfma_f32_16x16x32_bf16(Bt[n][k], At[m][k], acc[ai][bj][m][n], 0, 0, 0); __builtin_amdgcn_s_setprio(0); } while (0)
; #define PG8_WAIT_V(n) asm volatile("s_waitcnt vmcnt(" #n ")" ::: "memory")
; #define PG8_WAIT_L(n) asm volatile("s_waitcnt lgkmcnt(" #n ")" ::: "memory")
; #define PG8_BAR __builtin_amdgcn_s_barrier()
; #define PG8_SCHED __builtin_amdgcn_sched_barrier(0)
; template <class Epi, class Sched, bool ALIGN_EPI = false, bool SP2 = false, bool RS = false, bool BPRE = false>
; __device__ __forceinline__ void gemm_phase(PG8_LAS unsigned char* lds, const Gemm g, const Sched& S, const Epi& E, const float* rs_ss = nullptr, PG8_LAS float* rs_tab = nullptr) {
;     ...
;             PG8_WAIT_V(8); PG8_WAIT_L(0); PG8_BAR; PG8_MMA(1, 0, At, B0); PG8_MMA(1, 1, At, B1); PG8_BAR; PG8_SCHED;
;             PG8_LDB(B0, 1, 0); PG8_LDB(B1, 1, 1); PG8_SCHED; PG8_LDA(At, 1, 0); PG8_STAGE(PG8_SA(0, 1), a2 + hstep, voffA);
;             PG8_WAIT_V(8); PG8_WAIT_L(0); PG8_BAR; PG8_MMA(0, 0, At, B0); PG8_MMA(0, 1, At, B1); PG8_BAR; PG8_SCHED;
	s_setprio 1
	s_waitcnt lgkmcnt(0)
	v_mfma_f32_16x16x32_bf16 v[62:65], v[130:133], v[186:189], 0
	v_mfma_f32_16x16x32_bf16 v[58:61], v[152:155], v[186:189], 0
	v_mfma_f32_16x16x32_bf16 v[46:49], v[130:133], v[194:197], 0
	v_mfma_f32_16x16x32_bf16 v[42:45], v[152:155], v[194:197], 0
	v_mfma_f32_16x16x32_bf16 v[30:33], v[130:133], v[202:205], 0
	v_mfma_f32_16x16x32_bf16 v[26:29], v[152:155], v[202:205], 0
	v_mfma_f32_16x16x32_bf16 v[14:17], v[130:133], v[210:213], 0
	v_mfma_f32_16x16x32_bf16 v[10:13], v[152:155], v[210:213], 0
	v_mfma_f32_16x16x32_bf16 v[62:65], v[134:137], v[190:193], v[62:65]
	v_mfma_f32_16x16x32_bf16 v[58:61], v[156:159], v[190:193], v[58:61]
	v_mfma_f32_16x16x32_bf16 v[46:49], v[134:137], v[198:201], v[46:49]
	v_mfma_f32_16x16x32_bf16 v[42:45], v[156:159], v[198:201], v[42:45]
	v_mfma_f32_16x16x32_bf16 v[30:33], v[134:137], v[206:209], v[30:33]
	v_mfma_f32_16x16x32_bf16 v[26:29], v[156:159], v[206:209], v[26:29]
	v_mfma_f32_16x16x32_bf16 v[14:17], v[134:137], v[214:217], v[14:17]
	v_mfma_f32_16x16x32_bf16 v[10:13], v[156:159], v[214:217], v[10:13]
	s_setprio 0
	s_setprio 1
	v_mfma_f32_16x16x32_bf16 v[54:57], v[166:169], v[186:189], 0
	v_mfma_f32_16x16x32_bf16 v[50:53], v[174:177], v[186:189], 0
	v_mfma_f32_16x16x32_bf16 v[38:41], v[166:169], v[194:197], 0
	v_mfma_f32_16x16x32_bf16 v[34:37], v[174:177], v[194:197], 0
	v_mfma_f32_16x16x32_bf16 v[22:25], v[166:169], v[202:205], 0
	v_mfma_f32_16x16x32_bf16 v[18:21], v[174:177], v[202:205], 0
	v_mfma_f32_16x16x32_bf16 v[6:9], v[166:169], v[210:213], 0
	v_mfma_f32_16x16x32_bf16 v[2:5], v[174:177], v[210:213], 0
	v_mfma_f32_16x16x32_bf16 v[54:57], v[170:173], v[190:193], v[54:57]
	v_mfma_f32_16x16x32_bf16 v[50:53], v[182:185], v[190:193], v[50:53]
	v_mfma_f32_16x16x32_bf16 v[38:41], v[170:173], v[198:201], v[38:41]
	v_mfma_f32_16x16x32_bf16 v[34:37], v[182:185], v[198:201], v[34:37]
	v_mfma_f32_16x16x32_bf16 v[22:25], v[170:173], v[206:209], v[22:25]
	v_mfma_f32_16x16x32_bf16 v[18:21], v[182:185], v[206:209], v[18:21]
	v_mfma_f32_16x16x32_bf16 v[6:9], v[170:173], v[214:217], v[6:9]
	v_mfma_f32_16x16x32_bf16 v[2:5], v[182:185], v[214:217], v[2:5]
	s_setprio 0
	s_barrier
	s_add_i32 s90, 0, 0x18000
	v_add_u32_e32 v143, s90, v160
	s_add_i32 s91, 0, 0x1c000
	ds_read_b128 v[130:133], v143
	ds_read_b128 v[134:137], v143 offset:1024
	ds_read_b128 v[152:155], v143 offset:2048
	ds_read_b128 v[156:159], v143 offset:3072
	v_add_u32_e32 v143, s91, v160
	ds_read_b128 v[166:169], v143
	ds_read_b128 v[170:173], v143 offset:1024
	ds_read_b128 v[174:177], v143 offset:2048
	ds_read_b128 v[182:185], v143 offset:3072
	s_add_u32 s70, s70, 0x80000
	s_addc_u32 s71, s71, 0
	s_mov_b32 m0, s74
	v_lshl_add_u64 v[178:179], s[70:71], 0, v[138:139]
	ds_read_b128 v[186:189], v163 offset:32768
	ds_read_b128 v[190:193], v163 offset:33792
	ds_read_b128 v[194:197], v163 offset:34816
	ds_read_b128 v[198:201], v163 offset:35840
	ds_read_b128 v[202:205], v163 offset:36864
	ds_read_b128 v[206:209], v163 offset:37888
	ds_read_b128 v[210:213], v163 offset:38912
	ds_read_b128 v[214:217], v163 offset:39936
	global_load_lds_dwordx4 v[178:179], off
	v_lshl_add_u64 v[178:179], s[70:71], 0, v[140:141]
	s_mov_b32 m0, s75
	s_nop 0
	global_load_lds_dwordx4 v[178:179], off
	s_waitcnt vmcnt(8)
	s_waitcnt lgkmcnt(0)
	s_barrier
	s_setprio 1
	s_waitcnt lgkmcnt(0)
	v_mfma_f32_16x16x32_bf16 v[126:129], v[130:133], v[186:189], v[126:129]
	v_mfma_f32_16x16x32_bf16 v[122:125], v[152:155], v[186:189], v[122:125]
	v_mfma_f32_16x16x32_bf16 v[110:113], v[130:133], v[194:197], v[110:113]
	v_mfma_f32_16x16x32_bf16 v[106:109], v[152:155], v[194:197], v[106:109]
	v_mfma_f32_16x16x32_bf16 v[94:97], v[130:133], v[202:205], v[94:97]
	v_mfma_f32_16x16x32_bf16 v[90:93], v[152:155], v[202:205], v[90:93]
	v_mfma_f32_16x16x32_bf16 v[78:81], v[130:133], v[210:213], v[78:81]
	v_mfma_f32_16x16x32_bf16 v[74:77], v[152:155], v[210:213], v[74:77]
	v_mfma_f32_16x16x32_bf16 v[126:129], v[134:137], v[190:193], v[126:129]
	v_mfma_f32_16x16x32_bf16 v[122:125], v[156:159], v[190:193], v[122:125]
	v_mfma_f32_16x16x32_bf16 v[110:113], v[134:137], v[198:201], v[110:113]
	v_mfma_f32_16x16x32_bf16 v[106:109], v[156:159], v[198:201], v[106:109]
	v_mfma_f32_16x16x32_bf16 v[94:97], v[134:137], v[206:209], v[94:97]
	v_mfma_f32_16x16x32_bf16 v[90:93], v[156:159], v[206:209], v[90:93]
	v_mfma_f32_16x16x32_bf16 v[78:81], v[134:137], v[214:217], v[78:81]
	v_mfma_f32_16x16x32_bf16 v[74:77], v[156:159], v[214:217], v[74:77]
	s_setprio 0
	s_setprio 1
	v_mfma_f32_16x16x32_bf16 v[118:121], v[166:169], v[186:189], v[118:121]
	v_mfma_f32_16x16x32_bf16 v[114:117], v[174:177], v[186:189], v[114:117]
	v_mfma_f32_16x16x32_bf16 v[102:105], v[166:169], v[194:197], v[102:105]
	v_mfma_f32_16x16x32_bf16 v[98:101], v[174:177], v[194:197], v[98:101]
	v_mfma_f32_16x16x32_bf16 v[86:89], v[166:169], v[202:205], v[86:89]
	v_mfma_f32_16x16x32_bf16 v[82:85], v[174:177], v[202:205], v[82:85]
	v_mfma_f32_16x16x32_bf16 v[70:73], v[166:169], v[210:213], v[70:73]
	v_mfma_f32_16x16x32_bf16 v[66:69], v[174:177], v[210:213], v[66:69]
	v_mfma_f32_16x16x32_bf16 v[118:121], v[170:173], v[190:193], v[118:121]
	v_mfma_f32_16x16x32_bf16 v[114:117], v[182:185], v[190:193], v[114:117]
	v_mfma_f32_16x16x32_bf16 v[102:105], v[170:173], v[198:201], v[102:105]
	v_mfma_f32_16x16x32_bf16 v[98:101], v[182:185], v[198:201], v[98:101]
	v_mfma_f32_16x16x32_bf16 v[86:89], v[170:173], v[206:209], v[86:89]
	v_mfma_f32_16x16x32_bf16 v[82:85], v[182:185], v[206:209], v[82:85]
	v_mfma_f32_16x16x32_bf16 v[70:73], v[170:173], v[214:217], v[70:73]
	v_mfma_f32_16x16x32_bf16 v[66:69], v[182:185], v[214:217], v[66:69]
	s_setprio 0
	s_barrier
; #define PG8_STAGE(bufoff, gbase, voff) do { _Pragma("unroll") for (int _i = 0; _i < 2; ++_i) \
;         __builtin_amdgcn_global_load_lds((const unsigned*)((const char*)(gbase) + (voff)[_i]), (PG8_LAS unsigned*)(lds + (bufoff) + ldsw + _i * 8192), 16, 0, 0); } while (0)
; #define PG8_LDA(dst, b, h) do { _Pragma("unroll") for (int m = 0; m < 4; ++m) _Pragma("unroll") for (int k = 0; k < 2; ++k) dst[m][k] = *(const PG8_LAS bf16x8*)(lds + PG8_SA(b, h) + aoff + m * 2048 + k * 1024); } while (0)
; #define PG8_MMA(ai, bj, At, Bt) do { __builtin_amdgcn_s_setprio(1); _Pragma("unroll") for (int m = 0; m < 4; ++m) _Pragma("unroll") for (int n = 0; n < 2; ++n) _Pragma("unroll") for (int k = 0; k < 2; ++k) \
;         acc[ai][bj][m][n] = __builtin_amdgcn_mfma_f32_16x16x32_bf16(Bt[n][k], At[m][k], acc[ai][bj][m][n], 0, 0, 0); __builtin_amdgcn_s_setprio(0); } while (0)
; #define PG8_WAIT_V(n) asm volatile("s_waitcnt vmcnt(" #n ")" ::: "memory")
; #define PG8_WAIT_L(n) asm volatile("s_waitcnt lgkmcnt(" #n ")" ::: "memory")
; #define PG8_BAR __builtin_amdgcn_s_barrier()
; #define PG8_SCHED __builtin_amdgcn_sched_barrier(0)
; template <class Epi, class Sched, bool ALIGN_EPI = false, bool SP2 = false, bool RS = false, bool BPRE = false>
; __device__ __forceinline__ void gemm_phase(PG8_LAS unsigned char* lds, const Gemm g, const Sched& S, const Epi& E, const float* rs_ss = nullptr, PG8_LAS float* rs_tab = nullptr) {
;     ...
;         for (int t = 0; t < nt; t += 2) {
;     ...
;             PG8_LDA(At, 1, 1); PG8_STAGE(PG8_SB(1, 0), b3, voffB); PG8_STAGE(PG8_SB(1, 1), b3 + hstep, voffB); PG8_STAGE(PG8_SA(1, 0), a3, voffA);
;             PG8_WAIT_V(8); PG8_WAIT_L(0); PG8_BAR; PG8_MMA(1, 0, At, B0); PG8_MMA(1, 1, At, B1); PG8_BAR; PG8_SCHED;
	s_add_u32 s70, s60, 0x4000
	s_addc_u32 s71, s61, 0
	s_add_i32 s90, s90, s15
	v_lshl_add_u64 v[178:179], s[70:71], 0, v[138:139]
	s_mov_b32 m0, s90
	ds_read_b128 v[186:189], v163 offset:49152
	ds_read_b128 v[190:193], v163 offset:50176
	ds_read_b128 v[194:197], v163 offset:51200
	ds_read_b128 v[198:201], v163 offset:52224
	ds_read_b128 v[202:205], v163 offset:53248
	ds_read_b128 v[206:209], v163 offset:54272
	ds_read_b128 v[210:213], v163 offset:55296
	ds_read_b128 v[214:217], v163 offset:56320
	global_load_lds_dwordx4 v[178:179], off
	s_add_i32 m0, s90, 0x2000
	s_add_u32 s60, s60, 0x84000
	v_lshl_add_u64 v[178:179], s[70:71], 0, v[140:141]
	s_addc_u32 s61, s61, 0
	s_add_i32 s70, s91, s15
	global_load_lds_dwordx4 v[178:179], off
	v_lshl_add_u64 v[178:179], s[60:61], 0, v[138:139]
	s_mov_b32 m0, s70
	s_nop 0
	global_load_lds_dwordx4 v[178:179], off
	v_lshl_add_u64 v[178:179], s[60:61], 0, v[140:141]
	s_add_i32 m0, s70, 0x2000
	s_nop 0
	global_load_lds_dwordx4 v[178:179], off
	v_lshl_add_u64 v[178:179], s[58:59], 0, v[138:139]
	s_mov_b32 m0, s79
	s_nop 0
	global_load_lds_dwordx4 v[178:179], off
	v_lshl_add_u64 v[178:179], s[58:59], 0, v[140:141]
	s_mov_b32 m0, s80
	s_nop 0
	global_load_lds_dwordx4 v[178:179], off
	s_waitcnt vmcnt(8)
	s_waitcnt lgkmcnt(0)
	s_barrier
	s_setprio 1
	s_waitcnt lgkmcnt(0)
	v_mfma_f32_16x16x32_bf16 v[62:65], v[130:133], v[186:189], v[62:65]
	v_mfma_f32_16x16x32_bf16 v[58:61], v[152:155], v[186:189], v[58:61]
	v_mfma_f32_16x16x32_bf16 v[46:49], v[130:133], v[194:197], v[46:49]
	v_mfma_f32_16x16x32_bf16 v[42:45], v[152:155], v[194:197], v[42:45]
	v_mfma_f32_16x16x32_bf16 v[30:33], v[130:133], v[202:205], v[30:33]
	v_mfma_f32_16x16x32_bf16 v[26:29], v[152:155], v[202:205], v[26:29]
	v_mfma_f32_16x16x32_bf16 v[14:17], v[130:133], v[210:213], v[14:17]
	v_mfma_f32_16x16x32_bf16 v[10:13], v[152:155], v[210:213], v[10:13]
	v_mfma_f32_16x16x32_bf16 v[62:65], v[134:137], v[190:193], v[62:65]
	v_mfma_f32_16x16x32_bf16 v[58:61], v[156:159], v[190:193], v[58:61]
	v_mfma_f32_16x16x32_bf16 v[46:49], v[134:137], v[198:201], v[46:49]
	v_mfma_f32_16x16x32_bf16 v[42:45], v[156:159], v[198:201], v[42:45]
	v_mfma_f32_16x16x32_bf16 v[30:33], v[134:137], v[206:209], v[30:33]
	v_mfma_f32_16x16x32_bf16 v[26:29], v[156:159], v[206:209], v[26:29]
	v_mfma_f32_16x16x32_bf16 v[14:17], v[134:137], v[214:217], v[14:17]
	v_mfma_f32_16x16x32_bf16 v[10:13], v[156:159], v[214:217], v[10:13]
	s_setprio 0
	s_setprio 1
	v_mfma_f32_16x16x32_bf16 v[54:57], v[166:169], v[186:189], v[54:57]
	v_mfma_f32_16x16x32_bf16 v[50:53], v[174:177], v[186:189], v[50:53]
	v_mfma_f32_16x16x32_bf16 v[38:41], v[166:169], v[194:197], v[38:41]
	v_mfma_f32_16x16x32_bf16 v[34:37], v[174:177], v[194:197], v[34:37]
	v_mfma_f32_16x16x32_bf16 v[22:25], v[166:169], v[202:205], v[22:25]
	v_mfma_f32_16x16x32_bf16 v[18:21], v[174:177], v[202:205], v[18:21]
	v_mfma_f32_16x16x32_bf16 v[6:9], v[166:169], v[210:213], v[6:9]
	v_mfma_f32_16x16x32_bf16 v[2:5], v[174:177], v[210:213], v[2:5]
	v_mfma_f32_16x16x32_bf16 v[54:57], v[170:173], v[190:193], v[54:57]
	v_mfma_f32_16x16x32_bf16 v[50:53], v[182:185], v[190:193], v[50:53]
	v_mfma_f32_16x16x32_bf16 v[38:41], v[170:173], v[198:201], v[38:41]
	v_mfma_f32_16x16x32_bf16 v[34:37], v[182:185], v[198:201], v[34:37]
	v_mfma_f32_16x16x32_bf16 v[22:25], v[170:173], v[206:209], v[22:25]
	v_mfma_f32_16x16x32_bf16 v[18:21], v[182:185], v[206:209], v[18:21]
	v_mfma_f32_16x16x32_bf16 v[6:9], v[170:173], v[214:217], v[6:9]
	v_mfma_f32_16x16x32_bf16 v[2:5], v[182:185], v[214:217], v[2:5]
	s_setprio 0
	s_barrier
	s_add_i32 s89, s89, 2
	s_add_u32 s56, s56, 0x8000
	s_addc_u32 s57, s57, 0
	s_add_u32 s87, s87, 0x8000
	s_addc_u32 s88, s88, 0
